# rg_in epilogue gelu: tanh-argument polynomial refactored to x*(K+cK*x^2) with merged constants (256 fewer VALU per wave per gelu unit)
# baseline (speedup 1.0000x reference)
.LBB0_113:
	v_mov_b32_e32 v250, 0xbdd2d3e7
	s_cmp_lt_i32 s6, 4
	s_cselect_b64 s[36:37], -1, 0
	s_cmp_gt_i32 s6, 3
	s_cbranch_scc1 .LBB0_115
	v_mul_f32_e32 v155, v121, v121
	v_fmaak_f32 v155, v250, v155, 0xc0135761
	v_mul_f32_e32 v155, v121, v155
	v_exp_f32_e32 v155, v155
	v_mul_f32_e32 v147, v120, v120
	v_fmaak_f32 v147, v250, v147, 0xc0135761
	v_mul_f32_e32 v147, v120, v147
	v_add_f32_e32 v155, 1.0, v155
	v_rcp_f32_e32 v157, v155
	v_mul_f32_e32 v155, v126, v126
	v_exp_f32_e32 v147, v147
	v_fmaak_f32 v155, v250, v155, 0xc0135761
	v_mul_f32_e32 v155, v126, v155
	v_add_f32_e32 v147, 1.0, v147
	v_exp_f32_e32 v155, v155
	v_mul_f32_e32 v146, v124, v124
	v_rcp_f32_e32 v156, v147
	v_mul_f32_e32 v147, v125, v125
	v_fmaak_f32 v146, v250, v146, 0xc0135761
	v_fmaak_f32 v147, v250, v147, 0xc0135761
	v_mul_f32_e32 v146, v124, v146
	v_mul_f32_e32 v147, v125, v147
	v_add_f32_e32 v155, 1.0, v155
	v_rcp_f32_e32 v158, v155
	v_mul_f32_e32 v155, v122, v122
	v_exp_f32_e32 v146, v146
	v_exp_f32_e32 v147, v147
	v_fmaak_f32 v155, v250, v155, 0xc0135761
	v_mul_f32_e32 v155, v122, v155
	v_add_f32_e32 v146, 1.0, v146
	v_add_f32_e32 v147, 1.0, v147
	v_exp_f32_e32 v155, v155
	v_rcp_f32_e32 v146, v146
	v_rcp_f32_e32 v147, v147
	v_pk_mul_f32 v[120:121], v[120:121], v[156:157]
	v_add_f32_e32 v155, 1.0, v155
	v_rcp_f32_e32 v160, v155
	v_mul_f32_e32 v155, v127, v127
	v_pk_mul_f32 v[124:125], v[124:125], v[146:147]
	v_mul_f32_e32 v146, v123, v123
	v_fmaak_f32 v155, v250, v155, 0xc0135761
	v_fmaak_f32 v146, v250, v146, 0xc0135761
	v_mul_f32_e32 v155, v127, v155
	v_mul_f32_e32 v146, v123, v146
	v_exp_f32_e32 v155, v155
	v_exp_f32_e32 v146, v146
	v_add_f32_e32 v155, 1.0, v155
	v_add_f32_e32 v146, 1.0, v146
	v_rcp_f32_e32 v159, v155
	v_rcp_f32_e32 v161, v146
	v_pk_mul_f32 v[126:127], v[126:127], v[158:159]
	v_pk_mul_f32 v[122:123], v[122:123], v[160:161]
.LBB0_115:
	s_and_b64 s[8:9], s[36:37], exec
	v_lshl_add_u32 v146, s14, 8, v148
	v_readlane_b32 s8, v254, 37
	v_readlane_b32 s9, v254, 38
	v_ashrrev_i32_e32 v147, 31, v146
	s_cselect_b32 s9, s9, s35
	s_cselect_b32 s8, s8, s34
	v_lshlrev_b64 v[146:147], 11, v[146:147]
	s_lshl_b32 s6, s6, 9
	v_lshl_add_u64 v[146:147], s[8:9], 0, v[146:147]
	s_and_b32 s18, s6, 0x600
	v_lshl_add_u64 v[146:147], v[146:147], 0, s[18:19]
	s_mov_b32 s85, s19
	v_lshl_add_u64 v[146:147], v[146:147], 0, s[84:85]
	v_lshl_add_u64 v[146:147], v[146:147], 0, v[136:137]
	v_cvt_pk_bf16_f32 v124, v124, v125
	v_cvt_pk_bf16_f32 v125, v126, v127
	v_cvt_pk_bf16_f32 v126, v120, v121
	v_cvt_pk_bf16_f32 v127, v122, v123
	v_cndmask_b32_e64 v120, 0, 1, s[36:37]
	global_store_dwordx4 v[146:147], v[124:127], off sc0 sc1
	s_nop 1
	v_cmp_ne_u32_e64 s[6:7], 1, v120
	s_andn2_b64 vcc, exec, s[36:37]
	s_cbranch_vccnz .LBB0_117
	v_mul_f32_e32 v121, v112, v112
	v_fmaak_f32 v121, v250, v121, 0xc0135761
	v_mul_f32_e32 v121, v112, v121
	v_exp_f32_e32 v121, v121
	v_mul_f32_e32 v120, v116, v116
	v_fmaak_f32 v120, v250, v120, 0xc0135761
	v_add_f32_e32 v121, 1.0, v121
	v_rcp_f32_e32 v122, v121
	v_mul_f32_e32 v121, v117, v117
	v_fmaak_f32 v121, v250, v121, 0xc0135761
	v_mul_f32_e32 v120, v116, v120
	v_mul_f32_e32 v121, v117, v121
	v_mul_f32_e32 v125, v114, v114
	v_exp_f32_e32 v120, v120
	v_exp_f32_e32 v121, v121
	v_fmaak_f32 v125, v250, v125, 0xc0135761
	v_mul_f32_e32 v125, v114, v125
	v_add_f32_e32 v120, 1.0, v120
	v_add_f32_e32 v121, 1.0, v121
	v_exp_f32_e32 v125, v125
	v_rcp_f32_e32 v120, v120
	v_rcp_f32_e32 v121, v121
	v_mul_f32_e32 v123, v113, v113
	v_add_f32_e32 v125, 1.0, v125
	v_mul_f32_e32 v124, v118, v118
	v_rcp_f32_e32 v126, v125
	v_mul_f32_e32 v125, v119, v119
	v_pk_mul_f32 v[116:117], v[116:117], v[120:121]
	v_mul_f32_e32 v120, v115, v115
	v_fmaak_f32 v123, v250, v123, 0xc0135761
	v_fmaak_f32 v124, v250, v124, 0xc0135761
	v_fmaak_f32 v125, v250, v125, 0xc0135761
	v_fmaak_f32 v120, v250, v120, 0xc0135761
	v_mul_f32_e32 v123, v113, v123
	v_mul_f32_e32 v124, v118, v124
	v_mul_f32_e32 v125, v119, v125
	v_mul_f32_e32 v120, v115, v120
	v_exp_f32_e32 v123, v123
	v_exp_f32_e32 v124, v124
	v_exp_f32_e32 v125, v125
	v_exp_f32_e32 v120, v120
	v_add_f32_e32 v123, 1.0, v123
	v_add_f32_e32 v124, 1.0, v124
	v_add_f32_e32 v125, 1.0, v125
	v_add_f32_e32 v120, 1.0, v120
	v_rcp_f32_e32 v123, v123
	v_rcp_f32_e32 v124, v124
	v_rcp_f32_e32 v125, v125
	v_rcp_f32_e32 v127, v120
	v_pk_mul_f32 v[112:113], v[112:113], v[122:123]
	v_pk_mul_f32 v[118:119], v[118:119], v[124:125]
	v_pk_mul_f32 v[114:115], v[114:115], v[126:127]
.LBB0_117:
	s_mov_b64 s[8:9], 0x100
	v_cvt_pk_bf16_f32 v116, v116, v117
	v_cvt_pk_bf16_f32 v117, v118, v119
	v_cvt_pk_bf16_f32 v118, v112, v113
	v_cvt_pk_bf16_f32 v119, v114, v115
	v_lshl_add_u64 v[112:113], v[146:147], 0, s[8:9]
	global_store_dwordx4 v[112:113], v[116:119], off sc0 sc1
	s_nop 1
	s_and_b64 vcc, exec, s[6:7]
	s_cbranch_vccnz .LBB0_119
	v_mul_f32_e32 v113, v104, v104
	v_fmaak_f32 v113, v250, v113, 0xc0135761
	v_mul_f32_e32 v113, v104, v113
	v_exp_f32_e32 v113, v113
	v_mul_f32_e32 v112, v108, v108
	v_fmaak_f32 v112, v250, v112, 0xc0135761
	v_add_f32_e32 v113, 1.0, v113
	v_rcp_f32_e32 v114, v113
	v_mul_f32_e32 v113, v109, v109
	v_fmaak_f32 v113, v250, v113, 0xc0135761
	v_mul_f32_e32 v112, v108, v112
	v_mul_f32_e32 v113, v109, v113
	v_mul_f32_e32 v117, v106, v106
	v_exp_f32_e32 v112, v112
	v_exp_f32_e32 v113, v113
	v_fmaak_f32 v117, v250, v117, 0xc0135761
	v_mul_f32_e32 v117, v106, v117
	v_add_f32_e32 v112, 1.0, v112
	v_add_f32_e32 v113, 1.0, v113
	v_exp_f32_e32 v117, v117
	v_rcp_f32_e32 v112, v112
	v_rcp_f32_e32 v113, v113
	v_mul_f32_e32 v115, v105, v105
	v_add_f32_e32 v117, 1.0, v117
	v_mul_f32_e32 v116, v110, v110
	v_rcp_f32_e32 v118, v117
	v_mul_f32_e32 v117, v111, v111
	v_pk_mul_f32 v[108:109], v[108:109], v[112:113]
	v_mul_f32_e32 v112, v107, v107
	v_fmaak_f32 v115, v250, v115, 0xc0135761
	v_fmaak_f32 v116, v250, v116, 0xc0135761
	v_fmaak_f32 v117, v250, v117, 0xc0135761
	v_fmaak_f32 v112, v250, v112, 0xc0135761
	v_mul_f32_e32 v115, v105, v115
	v_mul_f32_e32 v116, v110, v116
	v_mul_f32_e32 v117, v111, v117
	v_mul_f32_e32 v112, v107, v112
	v_exp_f32_e32 v115, v115
	v_exp_f32_e32 v116, v116
	v_exp_f32_e32 v117, v117
	v_exp_f32_e32 v112, v112
	v_add_f32_e32 v115, 1.0, v115
	v_add_f32_e32 v116, 1.0, v116
	v_add_f32_e32 v117, 1.0, v117
	v_add_f32_e32 v112, 1.0, v112
	v_rcp_f32_e32 v115, v115
	v_rcp_f32_e32 v116, v116
	v_rcp_f32_e32 v117, v117
	v_rcp_f32_e32 v119, v112
	v_pk_mul_f32 v[104:105], v[104:105], v[114:115]
	v_pk_mul_f32 v[110:111], v[110:111], v[116:117]
	v_pk_mul_f32 v[106:107], v[106:107], v[118:119]
.LBB0_119:
	s_mov_b64 s[8:9], 0x8000
	v_lshl_add_u64 v[112:113], v[146:147], 0, s[8:9]
	v_cvt_pk_bf16_f32 v108, v108, v109
	v_cvt_pk_bf16_f32 v109, v110, v111
	v_cvt_pk_bf16_f32 v110, v104, v105
	v_cvt_pk_bf16_f32 v111, v106, v107
	s_and_b64 vcc, exec, s[6:7]
	global_store_dwordx4 v[112:113], v[108:111], off sc0 sc1
	s_nop 1
	s_cbranch_vccnz .LBB0_121
	v_mul_f32_e32 v105, v96, v96
	v_fmaak_f32 v105, v250, v105, 0xc0135761
	v_mul_f32_e32 v105, v96, v105
	v_exp_f32_e32 v105, v105
	v_mul_f32_e32 v104, v100, v100
	v_fmaak_f32 v104, v250, v104, 0xc0135761
	v_add_f32_e32 v105, 1.0, v105
	v_rcp_f32_e32 v106, v105
	v_mul_f32_e32 v105, v101, v101
	v_fmaak_f32 v105, v250, v105, 0xc0135761
	v_mul_f32_e32 v104, v100, v104
	v_mul_f32_e32 v105, v101, v105
	v_mul_f32_e32 v109, v98, v98
	v_exp_f32_e32 v104, v104
	v_exp_f32_e32 v105, v105
	v_fmaak_f32 v109, v250, v109, 0xc0135761
	v_mul_f32_e32 v109, v98, v109
	v_add_f32_e32 v104, 1.0, v104
	v_add_f32_e32 v105, 1.0, v105
	v_exp_f32_e32 v109, v109
	v_rcp_f32_e32 v104, v104
	v_rcp_f32_e32 v105, v105
	v_mul_f32_e32 v107, v97, v97
	v_add_f32_e32 v109, 1.0, v109
	v_mul_f32_e32 v108, v102, v102
	v_rcp_f32_e32 v110, v109
	v_mul_f32_e32 v109, v103, v103
	v_pk_mul_f32 v[100:101], v[100:101], v[104:105]
	v_mul_f32_e32 v104, v99, v99
	v_fmaak_f32 v107, v250, v107, 0xc0135761
	v_fmaak_f32 v108, v250, v108, 0xc0135761
	v_fmaak_f32 v109, v250, v109, 0xc0135761
	v_fmaak_f32 v104, v250, v104, 0xc0135761
	v_mul_f32_e32 v107, v97, v107
	v_mul_f32_e32 v108, v102, v108
	v_mul_f32_e32 v109, v103, v109
	v_mul_f32_e32 v104, v99, v104
	v_exp_f32_e32 v107, v107
	v_exp_f32_e32 v108, v108
	v_exp_f32_e32 v109, v109
	v_exp_f32_e32 v104, v104
	v_add_f32_e32 v107, 1.0, v107
	v_add_f32_e32 v108, 1.0, v108
	v_add_f32_e32 v109, 1.0, v109
	v_add_f32_e32 v104, 1.0, v104
	v_rcp_f32_e32 v107, v107
	v_rcp_f32_e32 v108, v108
	v_rcp_f32_e32 v109, v109
	v_rcp_f32_e32 v111, v104
	v_pk_mul_f32 v[96:97], v[96:97], v[106:107]
	v_pk_mul_f32 v[102:103], v[102:103], v[108:109]
	v_pk_mul_f32 v[98:99], v[98:99], v[110:111]
.LBB0_121:
	s_mov_b64 s[8:9], 0x8100
	v_cvt_pk_bf16_f32 v100, v100, v101
	v_cvt_pk_bf16_f32 v101, v102, v103
	v_cvt_pk_bf16_f32 v102, v96, v97
	v_cvt_pk_bf16_f32 v103, v98, v99
	v_lshl_add_u64 v[96:97], v[146:147], 0, s[8:9]
	global_store_dwordx4 v[96:97], v[100:103], off sc0 sc1
	s_nop 1
	s_and_b64 vcc, exec, s[6:7]
	s_cbranch_vccnz .LBB0_123
	v_mul_f32_e32 v97, v88, v88
	v_fmaak_f32 v97, v250, v97, 0xc0135761
	v_mul_f32_e32 v97, v88, v97
	v_exp_f32_e32 v97, v97
	v_mul_f32_e32 v96, v92, v92
	v_fmaak_f32 v96, v250, v96, 0xc0135761
	v_add_f32_e32 v97, 1.0, v97
	v_rcp_f32_e32 v98, v97
	v_mul_f32_e32 v97, v93, v93
	v_fmaak_f32 v97, v250, v97, 0xc0135761
	v_mul_f32_e32 v96, v92, v96
	v_mul_f32_e32 v97, v93, v97
	v_mul_f32_e32 v101, v90, v90
	v_exp_f32_e32 v96, v96
	v_exp_f32_e32 v97, v97
	v_fmaak_f32 v101, v250, v101, 0xc0135761
	v_mul_f32_e32 v101, v90, v101
	v_add_f32_e32 v96, 1.0, v96
	v_add_f32_e32 v97, 1.0, v97
	v_exp_f32_e32 v101, v101
	v_rcp_f32_e32 v96, v96
	v_rcp_f32_e32 v97, v97
	v_mul_f32_e32 v99, v89, v89
	v_add_f32_e32 v101, 1.0, v101
	v_mul_f32_e32 v100, v94, v94
	v_rcp_f32_e32 v102, v101
	v_mul_f32_e32 v101, v95, v95
	v_pk_mul_f32 v[92:93], v[92:93], v[96:97]
	v_mul_f32_e32 v96, v91, v91
	v_fmaak_f32 v99, v250, v99, 0xc0135761
	v_fmaak_f32 v100, v250, v100, 0xc0135761
	v_fmaak_f32 v101, v250, v101, 0xc0135761
	v_fmaak_f32 v96, v250, v96, 0xc0135761
	v_mul_f32_e32 v99, v89, v99
	v_mul_f32_e32 v100, v94, v100
	v_mul_f32_e32 v101, v95, v101
	v_mul_f32_e32 v96, v91, v96
	v_exp_f32_e32 v99, v99
	v_exp_f32_e32 v100, v100
	v_exp_f32_e32 v101, v101
	v_exp_f32_e32 v96, v96
	v_add_f32_e32 v99, 1.0, v99
	v_add_f32_e32 v100, 1.0, v100
	v_add_f32_e32 v101, 1.0, v101
	v_add_f32_e32 v96, 1.0, v96
	v_rcp_f32_e32 v99, v99
	v_rcp_f32_e32 v100, v100
	v_rcp_f32_e32 v101, v101
	v_rcp_f32_e32 v103, v96
	v_pk_mul_f32 v[88:89], v[88:89], v[98:99]
	v_pk_mul_f32 v[94:95], v[94:95], v[100:101]
	v_pk_mul_f32 v[90:91], v[90:91], v[102:103]
.LBB0_123:
	s_mov_b64 s[8:9], 0x10000
	v_lshl_add_u64 v[96:97], v[146:147], 0, s[8:9]
	v_cvt_pk_bf16_f32 v92, v92, v93
	v_cvt_pk_bf16_f32 v93, v94, v95
	v_cvt_pk_bf16_f32 v94, v88, v89
	v_cvt_pk_bf16_f32 v95, v90, v91
	s_and_b64 vcc, exec, s[6:7]
	global_store_dwordx4 v[96:97], v[92:95], off sc0 sc1
	s_nop 1
	s_cbranch_vccnz .LBB0_125
	v_mul_f32_e32 v89, v80, v80
	v_fmaak_f32 v89, v250, v89, 0xc0135761
	v_mul_f32_e32 v89, v80, v89
	v_exp_f32_e32 v89, v89
	v_mul_f32_e32 v88, v84, v84
	v_fmaak_f32 v88, v250, v88, 0xc0135761
	v_add_f32_e32 v89, 1.0, v89
	v_rcp_f32_e32 v90, v89
	v_mul_f32_e32 v89, v85, v85
	v_fmaak_f32 v89, v250, v89, 0xc0135761
	v_mul_f32_e32 v88, v84, v88
	v_mul_f32_e32 v89, v85, v89
	v_mul_f32_e32 v93, v82, v82
	v_exp_f32_e32 v88, v88
	v_exp_f32_e32 v89, v89
	v_fmaak_f32 v93, v250, v93, 0xc0135761
	v_mul_f32_e32 v93, v82, v93
	v_add_f32_e32 v88, 1.0, v88
	v_add_f32_e32 v89, 1.0, v89
	v_exp_f32_e32 v93, v93
	v_rcp_f32_e32 v88, v88
	v_rcp_f32_e32 v89, v89
	v_mul_f32_e32 v91, v81, v81
	v_add_f32_e32 v93, 1.0, v93
	v_mul_f32_e32 v92, v86, v86
	v_rcp_f32_e32 v94, v93
	v_mul_f32_e32 v93, v87, v87
	v_pk_mul_f32 v[84:85], v[84:85], v[88:89]
	v_mul_f32_e32 v88, v83, v83
	v_fmaak_f32 v91, v250, v91, 0xc0135761
	v_fmaak_f32 v92, v250, v92, 0xc0135761
	v_fmaak_f32 v93, v250, v93, 0xc0135761
	v_fmaak_f32 v88, v250, v88, 0xc0135761
	v_mul_f32_e32 v91, v81, v91
	v_mul_f32_e32 v92, v86, v92
	v_mul_f32_e32 v93, v87, v93
	v_mul_f32_e32 v88, v83, v88
	v_exp_f32_e32 v91, v91
	v_exp_f32_e32 v92, v92
	v_exp_f32_e32 v93, v93
	v_exp_f32_e32 v88, v88
	v_add_f32_e32 v91, 1.0, v91
	v_add_f32_e32 v92, 1.0, v92
	v_add_f32_e32 v93, 1.0, v93
	v_add_f32_e32 v88, 1.0, v88
	v_rcp_f32_e32 v91, v91
	v_rcp_f32_e32 v92, v92
	v_rcp_f32_e32 v93, v93
	v_rcp_f32_e32 v95, v88
	v_pk_mul_f32 v[80:81], v[80:81], v[90:91]
	v_pk_mul_f32 v[86:87], v[86:87], v[92:93]
	v_pk_mul_f32 v[82:83], v[82:83], v[94:95]
.LBB0_125:
	s_mov_b64 s[8:9], 0x10100
	v_cvt_pk_bf16_f32 v84, v84, v85
	v_cvt_pk_bf16_f32 v85, v86, v87
	v_cvt_pk_bf16_f32 v86, v80, v81
	v_cvt_pk_bf16_f32 v87, v82, v83
	v_lshl_add_u64 v[80:81], v[146:147], 0, s[8:9]
	global_store_dwordx4 v[80:81], v[84:87], off sc0 sc1
	s_nop 1
	s_and_b64 vcc, exec, s[6:7]
	s_cbranch_vccnz .LBB0_127
	v_mul_f32_e32 v81, v72, v72
	v_fmaak_f32 v81, v250, v81, 0xc0135761
	v_mul_f32_e32 v81, v72, v81
	v_exp_f32_e32 v81, v81
	v_mul_f32_e32 v80, v76, v76
	v_fmaak_f32 v80, v250, v80, 0xc0135761
	v_add_f32_e32 v81, 1.0, v81
	v_rcp_f32_e32 v82, v81
	v_mul_f32_e32 v81, v77, v77
	v_fmaak_f32 v81, v250, v81, 0xc0135761
	v_mul_f32_e32 v80, v76, v80
	v_mul_f32_e32 v81, v77, v81
	v_mul_f32_e32 v85, v74, v74
	v_exp_f32_e32 v80, v80
	v_exp_f32_e32 v81, v81
	v_fmaak_f32 v85, v250, v85, 0xc0135761
	v_mul_f32_e32 v85, v74, v85
	v_add_f32_e32 v80, 1.0, v80
	v_add_f32_e32 v81, 1.0, v81
	v_exp_f32_e32 v85, v85
	v_rcp_f32_e32 v80, v80
	v_rcp_f32_e32 v81, v81
	v_mul_f32_e32 v83, v73, v73
	v_add_f32_e32 v85, 1.0, v85
	v_mul_f32_e32 v84, v78, v78
	v_rcp_f32_e32 v86, v85
	v_mul_f32_e32 v85, v79, v79
	v_pk_mul_f32 v[76:77], v[76:77], v[80:81]
	v_mul_f32_e32 v80, v75, v75
	v_fmaak_f32 v83, v250, v83, 0xc0135761
	v_fmaak_f32 v84, v250, v84, 0xc0135761
	v_fmaak_f32 v85, v250, v85, 0xc0135761
	v_fmaak_f32 v80, v250, v80, 0xc0135761
	v_mul_f32_e32 v83, v73, v83
	v_mul_f32_e32 v84, v78, v84
	v_mul_f32_e32 v85, v79, v85
	v_mul_f32_e32 v80, v75, v80
	v_exp_f32_e32 v83, v83
	v_exp_f32_e32 v84, v84
	v_exp_f32_e32 v85, v85
	v_exp_f32_e32 v80, v80
	v_add_f32_e32 v83, 1.0, v83
	v_add_f32_e32 v84, 1.0, v84
	v_add_f32_e32 v85, 1.0, v85
	v_add_f32_e32 v80, 1.0, v80
	v_rcp_f32_e32 v83, v83
	v_rcp_f32_e32 v84, v84
	v_rcp_f32_e32 v85, v85
	v_rcp_f32_e32 v87, v80
	v_pk_mul_f32 v[72:73], v[72:73], v[82:83]
	v_pk_mul_f32 v[78:79], v[78:79], v[84:85]
	v_pk_mul_f32 v[74:75], v[74:75], v[86:87]
.LBB0_127:
	s_mov_b64 s[8:9], 0x18000
	v_lshl_add_u64 v[80:81], v[146:147], 0, s[8:9]
	v_cvt_pk_bf16_f32 v76, v76, v77
	v_cvt_pk_bf16_f32 v77, v78, v79
	v_cvt_pk_bf16_f32 v78, v72, v73
	v_cvt_pk_bf16_f32 v79, v74, v75
	s_and_b64 vcc, exec, s[6:7]
	global_store_dwordx4 v[80:81], v[76:79], off sc0 sc1
	s_nop 1
	s_cbranch_vccnz .LBB0_129
	v_mul_f32_e32 v73, v64, v64
	v_fmaak_f32 v73, v250, v73, 0xc0135761
	v_mul_f32_e32 v73, v64, v73
	v_exp_f32_e32 v73, v73
	v_mul_f32_e32 v72, v68, v68
	v_fmaak_f32 v72, v250, v72, 0xc0135761
	v_add_f32_e32 v73, 1.0, v73
	v_rcp_f32_e32 v74, v73
	v_mul_f32_e32 v73, v69, v69
	v_fmaak_f32 v73, v250, v73, 0xc0135761
	v_mul_f32_e32 v72, v68, v72
	v_mul_f32_e32 v73, v69, v73
	v_mul_f32_e32 v77, v66, v66
	v_exp_f32_e32 v72, v72
	v_exp_f32_e32 v73, v73
	v_fmaak_f32 v77, v250, v77, 0xc0135761
	v_mul_f32_e32 v77, v66, v77
	v_add_f32_e32 v72, 1.0, v72
	v_add_f32_e32 v73, 1.0, v73
	v_exp_f32_e32 v77, v77
	v_rcp_f32_e32 v72, v72
	v_rcp_f32_e32 v73, v73
	v_mul_f32_e32 v75, v65, v65
	v_add_f32_e32 v77, 1.0, v77
	v_mul_f32_e32 v76, v70, v70
	v_rcp_f32_e32 v78, v77
	v_mul_f32_e32 v77, v71, v71
	v_pk_mul_f32 v[68:69], v[68:69], v[72:73]
	v_mul_f32_e32 v72, v67, v67
	v_fmaak_f32 v75, v250, v75, 0xc0135761
	v_fmaak_f32 v76, v250, v76, 0xc0135761
	v_fmaak_f32 v77, v250, v77, 0xc0135761
	v_fmaak_f32 v72, v250, v72, 0xc0135761
	v_mul_f32_e32 v75, v65, v75
	v_mul_f32_e32 v76, v70, v76
	v_mul_f32_e32 v77, v71, v77
	v_mul_f32_e32 v72, v67, v72
	v_exp_f32_e32 v75, v75
	v_exp_f32_e32 v76, v76
	v_exp_f32_e32 v77, v77
	v_exp_f32_e32 v72, v72
	v_add_f32_e32 v75, 1.0, v75
	v_add_f32_e32 v76, 1.0, v76
	v_add_f32_e32 v77, 1.0, v77
	v_add_f32_e32 v72, 1.0, v72
	v_rcp_f32_e32 v75, v75
	v_rcp_f32_e32 v76, v76
	v_rcp_f32_e32 v77, v77
	v_rcp_f32_e32 v79, v72
	v_pk_mul_f32 v[64:65], v[64:65], v[74:75]
	v_pk_mul_f32 v[70:71], v[70:71], v[76:77]
	v_pk_mul_f32 v[66:67], v[66:67], v[78:79]
.LBB0_129:
	s_mov_b64 s[8:9], 0x18100
	v_cvt_pk_bf16_f32 v68, v68, v69
	v_cvt_pk_bf16_f32 v69, v70, v71
	v_cvt_pk_bf16_f32 v70, v64, v65
	v_cvt_pk_bf16_f32 v71, v66, v67
	v_lshl_add_u64 v[64:65], v[146:147], 0, s[8:9]
	global_store_dwordx4 v[64:65], v[68:71], off sc0 sc1
	s_nop 1
	s_and_b64 vcc, exec, s[6:7]
	s_cbranch_vccnz .LBB0_131
	v_mul_f32_e32 v65, v56, v56
	v_fmaak_f32 v65, v250, v65, 0xc0135761
	v_mul_f32_e32 v65, v56, v65
	v_exp_f32_e32 v65, v65
	v_mul_f32_e32 v64, v60, v60
	v_fmaak_f32 v64, v250, v64, 0xc0135761
	v_add_f32_e32 v65, 1.0, v65
	v_rcp_f32_e32 v66, v65
	v_mul_f32_e32 v65, v61, v61
	v_fmaak_f32 v65, v250, v65, 0xc0135761
	v_mul_f32_e32 v64, v60, v64
	v_mul_f32_e32 v65, v61, v65
	v_mul_f32_e32 v69, v58, v58
	v_exp_f32_e32 v64, v64
	v_exp_f32_e32 v65, v65
	v_fmaak_f32 v69, v250, v69, 0xc0135761
	v_mul_f32_e32 v69, v58, v69
	v_add_f32_e32 v64, 1.0, v64
	v_add_f32_e32 v65, 1.0, v65
	v_exp_f32_e32 v69, v69
	v_rcp_f32_e32 v64, v64
	v_rcp_f32_e32 v65, v65
	v_mul_f32_e32 v67, v57, v57
	v_add_f32_e32 v69, 1.0, v69
	v_mul_f32_e32 v68, v62, v62
	v_rcp_f32_e32 v70, v69
	v_mul_f32_e32 v69, v63, v63
	v_pk_mul_f32 v[60:61], v[60:61], v[64:65]
	v_mul_f32_e32 v64, v59, v59
	v_fmaak_f32 v67, v250, v67, 0xc0135761
	v_fmaak_f32 v68, v250, v68, 0xc0135761
	v_fmaak_f32 v69, v250, v69, 0xc0135761
	v_fmaak_f32 v64, v250, v64, 0xc0135761
	v_mul_f32_e32 v67, v57, v67
	v_mul_f32_e32 v68, v62, v68
	v_mul_f32_e32 v69, v63, v69
	v_mul_f32_e32 v64, v59, v64
	v_exp_f32_e32 v67, v67
	v_exp_f32_e32 v68, v68
	v_exp_f32_e32 v69, v69
	v_exp_f32_e32 v64, v64
	v_add_f32_e32 v67, 1.0, v67
	v_add_f32_e32 v68, 1.0, v68
	v_add_f32_e32 v69, 1.0, v69
	v_add_f32_e32 v64, 1.0, v64
	v_rcp_f32_e32 v67, v67
	v_rcp_f32_e32 v68, v68
	v_rcp_f32_e32 v69, v69
	v_rcp_f32_e32 v71, v64
	v_pk_mul_f32 v[56:57], v[56:57], v[66:67]
	v_pk_mul_f32 v[62:63], v[62:63], v[68:69]
	v_pk_mul_f32 v[58:59], v[58:59], v[70:71]
.LBB0_131:
	s_mov_b64 s[8:9], 0x40000
	v_lshl_add_u64 v[64:65], v[146:147], 0, s[8:9]
	v_cvt_pk_bf16_f32 v60, v60, v61
	v_cvt_pk_bf16_f32 v61, v62, v63
	v_cvt_pk_bf16_f32 v62, v56, v57
	v_cvt_pk_bf16_f32 v63, v58, v59
	s_and_b64 vcc, exec, s[6:7]
	global_store_dwordx4 v[64:65], v[60:63], off sc0 sc1
	s_nop 1
	s_cbranch_vccnz .LBB0_133
	v_mul_f32_e32 v57, v48, v48
	v_fmaak_f32 v57, v250, v57, 0xc0135761
	v_mul_f32_e32 v57, v48, v57
	v_exp_f32_e32 v57, v57
	v_mul_f32_e32 v56, v52, v52
	v_fmaak_f32 v56, v250, v56, 0xc0135761
	v_add_f32_e32 v57, 1.0, v57
	v_rcp_f32_e32 v58, v57
	v_mul_f32_e32 v57, v53, v53
	v_fmaak_f32 v57, v250, v57, 0xc0135761
	v_mul_f32_e32 v56, v52, v56
	v_mul_f32_e32 v57, v53, v57
	v_mul_f32_e32 v61, v50, v50
	v_exp_f32_e32 v56, v56
	v_exp_f32_e32 v57, v57
	v_fmaak_f32 v61, v250, v61, 0xc0135761
	v_mul_f32_e32 v61, v50, v61
	v_add_f32_e32 v56, 1.0, v56
	v_add_f32_e32 v57, 1.0, v57
	v_exp_f32_e32 v61, v61
	v_rcp_f32_e32 v56, v56
	v_rcp_f32_e32 v57, v57
	v_mul_f32_e32 v59, v49, v49
	v_add_f32_e32 v61, 1.0, v61
	v_mul_f32_e32 v60, v54, v54
	v_rcp_f32_e32 v62, v61
	v_mul_f32_e32 v61, v55, v55
	v_pk_mul_f32 v[52:53], v[52:53], v[56:57]
	v_mul_f32_e32 v56, v51, v51
	v_fmaak_f32 v59, v250, v59, 0xc0135761
	v_fmaak_f32 v60, v250, v60, 0xc0135761
	v_fmaak_f32 v61, v250, v61, 0xc0135761
	v_fmaak_f32 v56, v250, v56, 0xc0135761
	v_mul_f32_e32 v59, v49, v59
	v_mul_f32_e32 v60, v54, v60
	v_mul_f32_e32 v61, v55, v61
	v_mul_f32_e32 v56, v51, v56
	v_exp_f32_e32 v59, v59
	v_exp_f32_e32 v60, v60
	v_exp_f32_e32 v61, v61
	v_exp_f32_e32 v56, v56
	v_add_f32_e32 v59, 1.0, v59
	v_add_f32_e32 v60, 1.0, v60
	v_add_f32_e32 v61, 1.0, v61
	v_add_f32_e32 v56, 1.0, v56
	v_rcp_f32_e32 v59, v59
	v_rcp_f32_e32 v60, v60
	v_rcp_f32_e32 v61, v61
	v_rcp_f32_e32 v63, v56
	v_pk_mul_f32 v[48:49], v[48:49], v[58:59]
	v_pk_mul_f32 v[54:55], v[54:55], v[60:61]
	v_pk_mul_f32 v[50:51], v[50:51], v[62:63]
.LBB0_133:
	s_mov_b64 s[8:9], 0x40100
	v_cvt_pk_bf16_f32 v52, v52, v53
	v_cvt_pk_bf16_f32 v53, v54, v55
	v_cvt_pk_bf16_f32 v54, v48, v49
	v_cvt_pk_bf16_f32 v55, v50, v51
	v_lshl_add_u64 v[48:49], v[146:147], 0, s[8:9]
	global_store_dwordx4 v[48:49], v[52:55], off sc0 sc1
	s_nop 1
	s_and_b64 vcc, exec, s[6:7]
	s_cbranch_vccnz .LBB0_135
	v_mul_f32_e32 v49, v40, v40
	v_fmaak_f32 v49, v250, v49, 0xc0135761
	v_mul_f32_e32 v49, v40, v49
	v_exp_f32_e32 v49, v49
	v_mul_f32_e32 v48, v44, v44
	v_fmaak_f32 v48, v250, v48, 0xc0135761
	v_add_f32_e32 v49, 1.0, v49
	v_rcp_f32_e32 v50, v49
	v_mul_f32_e32 v49, v45, v45
	v_fmaak_f32 v49, v250, v49, 0xc0135761
	v_mul_f32_e32 v48, v44, v48
	v_mul_f32_e32 v49, v45, v49
	v_mul_f32_e32 v53, v42, v42
	v_exp_f32_e32 v48, v48
	v_exp_f32_e32 v49, v49
	v_fmaak_f32 v53, v250, v53, 0xc0135761
	v_mul_f32_e32 v53, v42, v53
	v_add_f32_e32 v48, 1.0, v48
	v_add_f32_e32 v49, 1.0, v49
	v_exp_f32_e32 v53, v53
	v_rcp_f32_e32 v48, v48
	v_rcp_f32_e32 v49, v49
	v_mul_f32_e32 v51, v41, v41
	v_add_f32_e32 v53, 1.0, v53
	v_mul_f32_e32 v52, v46, v46
	v_rcp_f32_e32 v54, v53
	v_mul_f32_e32 v53, v47, v47
	v_pk_mul_f32 v[44:45], v[44:45], v[48:49]
	v_mul_f32_e32 v48, v43, v43
	v_fmaak_f32 v51, v250, v51, 0xc0135761
	v_fmaak_f32 v52, v250, v52, 0xc0135761
	v_fmaak_f32 v53, v250, v53, 0xc0135761
	v_fmaak_f32 v48, v250, v48, 0xc0135761
	v_mul_f32_e32 v51, v41, v51
	v_mul_f32_e32 v52, v46, v52
	v_mul_f32_e32 v53, v47, v53
	v_mul_f32_e32 v48, v43, v48
	v_exp_f32_e32 v51, v51
	v_exp_f32_e32 v52, v52
	v_exp_f32_e32 v53, v53
	v_exp_f32_e32 v48, v48
	v_add_f32_e32 v51, 1.0, v51
	v_add_f32_e32 v52, 1.0, v52
	v_add_f32_e32 v53, 1.0, v53
	v_add_f32_e32 v48, 1.0, v48
	v_rcp_f32_e32 v51, v51
	v_rcp_f32_e32 v52, v52
	v_rcp_f32_e32 v53, v53
	v_rcp_f32_e32 v55, v48
	v_pk_mul_f32 v[40:41], v[40:41], v[50:51]
	v_pk_mul_f32 v[46:47], v[46:47], v[52:53]
	v_pk_mul_f32 v[42:43], v[42:43], v[54:55]
.LBB0_135:
	s_mov_b64 s[8:9], 0x48000
	v_lshl_add_u64 v[48:49], v[146:147], 0, s[8:9]
	v_cvt_pk_bf16_f32 v44, v44, v45
	v_cvt_pk_bf16_f32 v45, v46, v47
	v_cvt_pk_bf16_f32 v46, v40, v41
	v_cvt_pk_bf16_f32 v47, v42, v43
	s_and_b64 vcc, exec, s[6:7]
	global_store_dwordx4 v[48:49], v[44:47], off sc0 sc1
	s_nop 1
	s_cbranch_vccnz .LBB0_137
	v_mul_f32_e32 v41, v32, v32
	v_fmaak_f32 v41, v250, v41, 0xc0135761
	v_mul_f32_e32 v41, v32, v41
	v_exp_f32_e32 v41, v41
	v_mul_f32_e32 v40, v36, v36
	v_fmaak_f32 v40, v250, v40, 0xc0135761
	v_add_f32_e32 v41, 1.0, v41
	v_rcp_f32_e32 v42, v41
	v_mul_f32_e32 v41, v37, v37
	v_fmaak_f32 v41, v250, v41, 0xc0135761
	v_mul_f32_e32 v40, v36, v40
	v_mul_f32_e32 v41, v37, v41
	v_mul_f32_e32 v45, v34, v34
	v_exp_f32_e32 v40, v40
	v_exp_f32_e32 v41, v41
	v_fmaak_f32 v45, v250, v45, 0xc0135761
	v_mul_f32_e32 v45, v34, v45
	v_add_f32_e32 v40, 1.0, v40
	v_add_f32_e32 v41, 1.0, v41
	v_exp_f32_e32 v45, v45
	v_rcp_f32_e32 v40, v40
	v_rcp_f32_e32 v41, v41
	v_mul_f32_e32 v43, v33, v33
	v_add_f32_e32 v45, 1.0, v45
	v_mul_f32_e32 v44, v38, v38
	v_rcp_f32_e32 v46, v45
	v_mul_f32_e32 v45, v39, v39
	v_pk_mul_f32 v[36:37], v[36:37], v[40:41]
	v_mul_f32_e32 v40, v35, v35
	v_fmaak_f32 v43, v250, v43, 0xc0135761
	v_fmaak_f32 v44, v250, v44, 0xc0135761
	v_fmaak_f32 v45, v250, v45, 0xc0135761
	v_fmaak_f32 v40, v250, v40, 0xc0135761
	v_mul_f32_e32 v43, v33, v43
	v_mul_f32_e32 v44, v38, v44
	v_mul_f32_e32 v45, v39, v45
	v_mul_f32_e32 v40, v35, v40
	v_exp_f32_e32 v43, v43
	v_exp_f32_e32 v44, v44
	v_exp_f32_e32 v45, v45
	v_exp_f32_e32 v40, v40
	v_add_f32_e32 v43, 1.0, v43
	v_add_f32_e32 v44, 1.0, v44
	v_add_f32_e32 v45, 1.0, v45
	v_add_f32_e32 v40, 1.0, v40
	v_rcp_f32_e32 v43, v43
	v_rcp_f32_e32 v44, v44
	v_rcp_f32_e32 v45, v45
	v_rcp_f32_e32 v47, v40
	v_pk_mul_f32 v[32:33], v[32:33], v[42:43]
	v_pk_mul_f32 v[38:39], v[38:39], v[44:45]
	v_pk_mul_f32 v[34:35], v[34:35], v[46:47]
.LBB0_137:
	s_mov_b64 s[8:9], 0x48100
	v_cvt_pk_bf16_f32 v36, v36, v37
	v_cvt_pk_bf16_f32 v37, v38, v39
	v_cvt_pk_bf16_f32 v38, v32, v33
	v_cvt_pk_bf16_f32 v39, v34, v35
	v_lshl_add_u64 v[32:33], v[146:147], 0, s[8:9]
	global_store_dwordx4 v[32:33], v[36:39], off sc0 sc1
	s_nop 1
	s_and_b64 vcc, exec, s[6:7]
	s_cbranch_vccnz .LBB0_139
	v_mul_f32_e32 v33, v24, v24
	v_fmaak_f32 v33, v250, v33, 0xc0135761
	v_mul_f32_e32 v33, v24, v33
	v_exp_f32_e32 v33, v33
	v_mul_f32_e32 v32, v28, v28
	v_fmaak_f32 v32, v250, v32, 0xc0135761
	v_add_f32_e32 v33, 1.0, v33
	v_rcp_f32_e32 v34, v33
	v_mul_f32_e32 v33, v29, v29
	v_fmaak_f32 v33, v250, v33, 0xc0135761
	v_mul_f32_e32 v32, v28, v32
	v_mul_f32_e32 v33, v29, v33
	v_mul_f32_e32 v37, v26, v26
	v_exp_f32_e32 v32, v32
	v_exp_f32_e32 v33, v33
	v_fmaak_f32 v37, v250, v37, 0xc0135761
	v_mul_f32_e32 v37, v26, v37
	v_add_f32_e32 v32, 1.0, v32
	v_add_f32_e32 v33, 1.0, v33
	v_exp_f32_e32 v37, v37
	v_rcp_f32_e32 v32, v32
	v_rcp_f32_e32 v33, v33
	v_mul_f32_e32 v35, v25, v25
	v_add_f32_e32 v37, 1.0, v37
	v_mul_f32_e32 v36, v30, v30
	v_rcp_f32_e32 v38, v37
	v_mul_f32_e32 v37, v31, v31
	v_pk_mul_f32 v[28:29], v[28:29], v[32:33]
	v_mul_f32_e32 v32, v27, v27
	v_fmaak_f32 v35, v250, v35, 0xc0135761
	v_fmaak_f32 v36, v250, v36, 0xc0135761
	v_fmaak_f32 v37, v250, v37, 0xc0135761
	v_fmaak_f32 v32, v250, v32, 0xc0135761
	v_mul_f32_e32 v35, v25, v35
	v_mul_f32_e32 v36, v30, v36
	v_mul_f32_e32 v37, v31, v37
	v_mul_f32_e32 v32, v27, v32
	v_exp_f32_e32 v35, v35
	v_exp_f32_e32 v36, v36
	v_exp_f32_e32 v37, v37
	v_exp_f32_e32 v32, v32
	v_add_f32_e32 v35, 1.0, v35
	v_add_f32_e32 v36, 1.0, v36
	v_add_f32_e32 v37, 1.0, v37
	v_add_f32_e32 v32, 1.0, v32
	v_rcp_f32_e32 v35, v35
	v_rcp_f32_e32 v36, v36
	v_rcp_f32_e32 v37, v37
	v_rcp_f32_e32 v39, v32
	v_pk_mul_f32 v[24:25], v[24:25], v[34:35]
	v_pk_mul_f32 v[30:31], v[30:31], v[36:37]
	v_pk_mul_f32 v[26:27], v[26:27], v[38:39]
.LBB0_139:
	s_mov_b64 s[8:9], 0x50000
	v_lshl_add_u64 v[32:33], v[146:147], 0, s[8:9]
	v_cvt_pk_bf16_f32 v28, v28, v29
	v_cvt_pk_bf16_f32 v29, v30, v31
	v_cvt_pk_bf16_f32 v30, v24, v25
	v_cvt_pk_bf16_f32 v31, v26, v27
	s_and_b64 vcc, exec, s[6:7]
	global_store_dwordx4 v[32:33], v[28:31], off sc0 sc1
	s_nop 1
	s_cbranch_vccnz .LBB0_141
	v_mul_f32_e32 v25, v16, v16
	v_fmaak_f32 v25, v250, v25, 0xc0135761
	v_mul_f32_e32 v25, v16, v25
	v_exp_f32_e32 v25, v25
	v_mul_f32_e32 v24, v20, v20
	v_fmaak_f32 v24, v250, v24, 0xc0135761
	v_add_f32_e32 v25, 1.0, v25
	v_rcp_f32_e32 v26, v25
	v_mul_f32_e32 v25, v21, v21
	v_fmaak_f32 v25, v250, v25, 0xc0135761
	v_mul_f32_e32 v24, v20, v24
	v_mul_f32_e32 v25, v21, v25
	v_mul_f32_e32 v29, v18, v18
	v_exp_f32_e32 v24, v24
	v_exp_f32_e32 v25, v25
	v_fmaak_f32 v29, v250, v29, 0xc0135761
	v_mul_f32_e32 v29, v18, v29
	v_add_f32_e32 v24, 1.0, v24
	v_add_f32_e32 v25, 1.0, v25
	v_exp_f32_e32 v29, v29
	v_rcp_f32_e32 v24, v24
	v_rcp_f32_e32 v25, v25
	v_mul_f32_e32 v27, v17, v17
	v_add_f32_e32 v29, 1.0, v29
	v_mul_f32_e32 v28, v22, v22
	v_rcp_f32_e32 v30, v29
	v_mul_f32_e32 v29, v23, v23
	v_pk_mul_f32 v[20:21], v[20:21], v[24:25]
	v_mul_f32_e32 v24, v19, v19
	v_fmaak_f32 v27, v250, v27, 0xc0135761
	v_fmaak_f32 v28, v250, v28, 0xc0135761
	v_fmaak_f32 v29, v250, v29, 0xc0135761
	v_fmaak_f32 v24, v250, v24, 0xc0135761
	v_mul_f32_e32 v27, v17, v27
	v_mul_f32_e32 v28, v22, v28
	v_mul_f32_e32 v29, v23, v29
	v_mul_f32_e32 v24, v19, v24
	v_exp_f32_e32 v27, v27
	v_exp_f32_e32 v28, v28
	v_exp_f32_e32 v29, v29
	v_exp_f32_e32 v24, v24
	v_add_f32_e32 v27, 1.0, v27
	v_add_f32_e32 v28, 1.0, v28
	v_add_f32_e32 v29, 1.0, v29
	v_add_f32_e32 v24, 1.0, v24
	v_rcp_f32_e32 v27, v27
	v_rcp_f32_e32 v28, v28
	v_rcp_f32_e32 v29, v29
	v_rcp_f32_e32 v31, v24
	v_pk_mul_f32 v[16:17], v[16:17], v[26:27]
	v_pk_mul_f32 v[22:23], v[22:23], v[28:29]
	v_pk_mul_f32 v[18:19], v[18:19], v[30:31]
.LBB0_141:
	s_mov_b64 s[8:9], 0x50100
	v_cvt_pk_bf16_f32 v20, v20, v21
	v_cvt_pk_bf16_f32 v21, v22, v23
	v_cvt_pk_bf16_f32 v22, v16, v17
	v_cvt_pk_bf16_f32 v23, v18, v19
	v_lshl_add_u64 v[16:17], v[146:147], 0, s[8:9]
	global_store_dwordx4 v[16:17], v[20:23], off sc0 sc1
	s_nop 1
	s_and_b64 vcc, exec, s[6:7]
	s_cbranch_vccnz .LBB0_143
	v_mul_f32_e32 v17, v8, v8
	v_fmaak_f32 v17, v250, v17, 0xc0135761
	v_mul_f32_e32 v17, v8, v17
	v_exp_f32_e32 v17, v17
	v_mul_f32_e32 v16, v12, v12
	v_fmaak_f32 v16, v250, v16, 0xc0135761
	v_add_f32_e32 v17, 1.0, v17
	v_rcp_f32_e32 v18, v17
	v_mul_f32_e32 v17, v13, v13
	v_fmaak_f32 v17, v250, v17, 0xc0135761
	v_mul_f32_e32 v16, v12, v16
	v_mul_f32_e32 v17, v13, v17
	v_mul_f32_e32 v21, v10, v10
	v_exp_f32_e32 v16, v16
	v_exp_f32_e32 v17, v17
	v_fmaak_f32 v21, v250, v21, 0xc0135761
	v_mul_f32_e32 v21, v10, v21
	v_add_f32_e32 v16, 1.0, v16
	v_add_f32_e32 v17, 1.0, v17
	v_exp_f32_e32 v21, v21
	v_rcp_f32_e32 v16, v16
	v_rcp_f32_e32 v17, v17
	v_mul_f32_e32 v19, v9, v9
	v_add_f32_e32 v21, 1.0, v21
	v_mul_f32_e32 v20, v14, v14
	v_rcp_f32_e32 v22, v21
	v_mul_f32_e32 v21, v15, v15
	v_pk_mul_f32 v[12:13], v[12:13], v[16:17]
	v_mul_f32_e32 v16, v11, v11
	v_fmaak_f32 v19, v250, v19, 0xc0135761
	v_fmaak_f32 v20, v250, v20, 0xc0135761
	v_fmaak_f32 v21, v250, v21, 0xc0135761
	v_fmaak_f32 v16, v250, v16, 0xc0135761
	v_mul_f32_e32 v19, v9, v19
	v_mul_f32_e32 v20, v14, v20
	v_mul_f32_e32 v21, v15, v21
	v_mul_f32_e32 v16, v11, v16
	v_exp_f32_e32 v19, v19
	v_exp_f32_e32 v20, v20
	v_exp_f32_e32 v21, v21
	v_exp_f32_e32 v16, v16
	v_add_f32_e32 v19, 1.0, v19
	v_add_f32_e32 v20, 1.0, v20
	v_add_f32_e32 v21, 1.0, v21
	v_add_f32_e32 v16, 1.0, v16
	v_rcp_f32_e32 v19, v19
	v_rcp_f32_e32 v20, v20
	v_rcp_f32_e32 v21, v21
	v_rcp_f32_e32 v23, v16
	v_pk_mul_f32 v[8:9], v[8:9], v[18:19]
	v_pk_mul_f32 v[14:15], v[14:15], v[20:21]
	v_pk_mul_f32 v[10:11], v[10:11], v[22:23]
.LBB0_143:
	s_mov_b64 s[8:9], 0x58000
	v_lshl_add_u64 v[16:17], v[146:147], 0, s[8:9]
	v_cvt_pk_bf16_f32 v12, v12, v13
	v_cvt_pk_bf16_f32 v13, v14, v15
	v_cvt_pk_bf16_f32 v14, v8, v9
	v_cvt_pk_bf16_f32 v15, v10, v11
	s_and_b64 vcc, exec, s[6:7]
	global_store_dwordx4 v[16:17], v[12:15], off sc0 sc1
	s_nop 1
	s_cbranch_vccnz .LBB0_145
	v_mul_f32_e32 v9, v0, v0
	v_fmaak_f32 v9, v250, v9, 0xc0135761
	v_mul_f32_e32 v9, v0, v9
	v_exp_f32_e32 v9, v9
	v_mul_f32_e32 v8, v4, v4
	v_fmaak_f32 v8, v250, v8, 0xc0135761
	v_add_f32_e32 v9, 1.0, v9
	v_rcp_f32_e32 v10, v9
	v_mul_f32_e32 v9, v5, v5
	v_fmaak_f32 v9, v250, v9, 0xc0135761
	v_mul_f32_e32 v8, v4, v8
	v_mul_f32_e32 v9, v5, v9
	v_mul_f32_e32 v13, v2, v2
	v_exp_f32_e32 v8, v8
	v_exp_f32_e32 v9, v9
	v_fmaak_f32 v13, v250, v13, 0xc0135761
	v_mul_f32_e32 v13, v2, v13
	v_add_f32_e32 v8, 1.0, v8
	v_add_f32_e32 v9, 1.0, v9
	v_exp_f32_e32 v13, v13
	v_rcp_f32_e32 v8, v8
	v_rcp_f32_e32 v9, v9
	v_mul_f32_e32 v11, v1, v1
	v_add_f32_e32 v13, 1.0, v13
	v_mul_f32_e32 v12, v6, v6
	v_rcp_f32_e32 v14, v13
	v_mul_f32_e32 v13, v7, v7
	v_pk_mul_f32 v[4:5], v[4:5], v[8:9]
	v_mul_f32_e32 v8, v3, v3
	v_fmaak_f32 v11, v250, v11, 0xc0135761
	v_fmaak_f32 v12, v250, v12, 0xc0135761
	v_fmaak_f32 v13, v250, v13, 0xc0135761
	v_fmaak_f32 v8, v250, v8, 0xc0135761
	v_mul_f32_e32 v11, v1, v11
	v_mul_f32_e32 v12, v6, v12
	v_mul_f32_e32 v13, v7, v13
	v_mul_f32_e32 v8, v3, v8
	v_exp_f32_e32 v11, v11
	v_exp_f32_e32 v12, v12
	v_exp_f32_e32 v13, v13
	v_exp_f32_e32 v8, v8
	v_add_f32_e32 v11, 1.0, v11
	v_add_f32_e32 v12, 1.0, v12
	v_add_f32_e32 v13, 1.0, v13
	v_add_f32_e32 v8, 1.0, v8
	v_rcp_f32_e32 v11, v11
	v_rcp_f32_e32 v12, v12
	v_rcp_f32_e32 v13, v13
	v_rcp_f32_e32 v15, v8
	v_pk_mul_f32 v[0:1], v[0:1], v[10:11]
	v_pk_mul_f32 v[6:7], v[6:7], v[12:13]
	v_pk_mul_f32 v[2:3], v[2:3], v[14:15]
